# input-projection epilogue stores (218 MB PROJ stream) non-temporal
# baseline (speedup 1.0000x reference)
; #define LAS __attribute__((address_space(3)))
; __device__ __forceinline__ unsigned pk2(float lo, float hi) { f32x2 f = {lo, hi}; bf16x2_t b = __builtin_convertvector(f, bf16x2_t); return __builtin_bit_cast(unsigned, b); }
; __device__ __forceinline__ float row_rstd(const LAS float* RS, int ord, int lrow) {
;     const float ssum = RS[ord * 256 + lrow] + RS[2048 + ord * 256 + lrow];
;     return 1.0f / sqrtf(ssum * (1.0f / D) + 1e-6f);
; }
;     __device__ __forceinline__ void operator()(const AccT& acc, const Unit& u, int wr, int wc, int fr, int fq) const {
;     ...
;         if (!rot) {
; #pragma unroll
;             for (int ai = 0; ai < 2; ++ai)
; #pragma unroll
;                 for (int m = 0; m < 4; ++m) {
;                     const int row = row0 + ai * 128 + m * 16;
;                     const float rstd = row_rstd(RS, u.ord, wr * 64 + fr + ai * 128 + m * 16);
;                     bf16_t* rowp = P + (size_t)row * INW + col0;
; #pragma unroll
;                     for (int bj = 0; bj < 2; ++bj) {
;                         const f32x4 v0 = acc[ai][bj][m][0] * rstd, v1 = acc[ai][bj][m][1] * rstd;
;                         u32x4 w; w.x = pk2(v0[0], v0[1]); w.y = pk2(v0[2], v0[3]); w.z = pk2(v1[0], v1[1]); w.w = pk2(v1[2], v1[3]);
;                         if (isgr) {
;                             const int sp = row & (S - 1), tl = sp & 127;
;                             bf16_t* gb = GRL + ((size_t)(((row >> 12) * 8 + (pn - 28)) * 32 + (sp >> 7))) * 32768
;                                        + (size_t)((((((bj * 4 + wc) * 4 + fq) * 4 + (tl >> 5)) * 2) * 32 + (tl & 31)) * 4);
;                             u32x2 lo2; lo2.x = w.x; lo2.y = w.y; u32x2 hi2; hi2.x = w.z; hi2.y = w.w;
;                             *(u32x2*)gb = lo2; *(u32x2*)(gb + 32 * 4) = hi2;
;                         } else *(u32x4*)(rowp + bj * 128) = w;
;                     }
;                 }
.LBB0_305:
	s_sub_i32 s25, s92, 28
	s_cmp_gt_u32 s25, 7
	s_cselect_b64 s[36:37], -1, 0
	s_lshl_b32 s0, s29, 10
	v_add_u32_e32 v138, s0, v233
	ds_read2st64_b32 v[128:129], v138 offset1:32
	s_waitcnt lgkmcnt(0)
	v_add_f32_e32 v128, v128, v129
	v_fmamk_f32 v128, v128, 0x3a000000, v236
	v_mul_f32_e32 v129, 0x4f800000, v128
	v_cmp_gt_f32_e32 vcc, s73, v128
	s_nop 1
	v_cndmask_b32_e32 v128, v128, v129, vcc
	v_rsq_f32_e32 v129, v128
	s_nop 0
	s_nop 0
	s_nop 1
	s_nop 1
	s_nop 1
	v_mov_b32_e32 v134, v129
	v_mov_b64_e32 v[128:129], s[18:19]
	v_mad_i64_i32 v[128:129], s[0:1], v227, s74, v[128:129]
	v_lshl_add_u64 v[132:133], v[192:193], 1, v[128:129]
	v_pk_mul_f32 v[130:131], v[126:127], v[134:135] op_sel_hi:[1,0]
	v_pk_mul_f32 v[128:129], v[124:125], v[134:135] op_sel_hi:[1,0]
	v_pk_mul_f32 v[136:137], v[122:123], v[134:135] op_sel_hi:[1,0]
	v_pk_mul_f32 v[140:141], v[120:121], v[134:135] op_sel_hi:[1,0]
	v_cvt_pk_bf16_f32 v128, v128, v129
	v_cvt_pk_bf16_f32 v129, v130, v131
	v_cvt_pk_bf16_f32 v130, v140, v141
	v_cvt_pk_bf16_f32 v131, v136, v137
	s_mov_b64 s[0:1], -1
	s_and_b64 vcc, exec, s[36:37]
	s_cbranch_vccz .LBB0_307
	global_store_dwordx4 v[132:133], v[128:131], off nt
	s_mov_b64 s[0:1], 0
.LBB0_307:
	s_ashr_i32 s11, s10, 9
	s_and_b32 s11, s11, 0x7fffff8
	s_add_i32 s11, s11, s25
	s_lshl_b32 s11, s11, 5
	s_bfe_u32 s10, s10, 0x50007
	s_or_b32 s10, s11, s10
	s_ashr_i32 s11, s10, 31
	s_lshl_b64 s[14:15], s[10:11], 16
	s_andn2_b64 vcc, exec, s[0:1]
	v_lshl_add_u64 v[136:137], v[220:221], 0, s[14:15]
	s_cbranch_vccnz .LBB0_309
	global_store_dwordx2 v[136:137], v[128:129], off nt
	global_store_dwordx2 v[136:137], v[130:131], off offset:256 nt
.LBB0_309:
	v_mov_b32_e32 v135, v134
	v_mov_b32_e32 v128, v134
	v_mov_b32_e32 v129, v134
	v_pk_mul_f32 v[130:131], v[118:119], v[128:129]
	v_pk_mul_f32 v[140:141], v[116:117], v[134:135]
	v_pk_mul_f32 v[134:135], v[112:113], v[134:135]
	v_pk_mul_f32 v[142:143], v[114:115], v[128:129]
	v_cvt_pk_bf16_f32 v129, v130, v131
	v_cvt_pk_bf16_f32 v130, v134, v135
	v_cndmask_b32_e64 v134, 0, 1, s[36:37]
	v_cvt_pk_bf16_f32 v128, v140, v141
	v_cvt_pk_bf16_f32 v131, v142, v143
	v_cmp_ne_u32_e64 s[10:11], 1, v134
	s_andn2_b64 vcc, exec, s[36:37]
	s_mov_b64 s[0:1], -1
	s_cbranch_vccnz .LBB0_311
	s_mov_b64 s[0:1], 0
	global_store_dwordx4 v[132:133], v[128:131], off offset:256 nt
.LBB0_311:
	s_andn2_b64 vcc, exec, s[0:1]
	s_cbranch_vccnz .LBB0_313
	v_add_co_u32_e32 v132, vcc, 0x8000, v136
	s_nop 1
	v_addc_co_u32_e32 v133, vcc, 0, v137, vcc
	global_store_dwordx2 v[132:133], v[128:129], off nt
	global_store_dwordx2 v[132:133], v[130:131], off offset:256 nt
.LBB0_313:
	v_add_u32_e32 v140, 64, v138
	ds_read2st64_b32 v[128:129], v140 offset1:32
	s_waitcnt lgkmcnt(0)
	v_add_f32_e32 v128, v128, v129
	v_fmamk_f32 v128, v128, 0x3a000000, v236
	v_mul_f32_e32 v129, 0x4f800000, v128
	v_cmp_gt_f32_e32 vcc, s73, v128
	s_nop 1
	v_cndmask_b32_e32 v128, v128, v129, vcc
	v_rsq_f32_e32 v129, v128
	s_nop 0
	s_nop 0
	s_nop 1
	s_nop 1
	v_or_b32_e32 v131, 16, v227
	s_nop 0
	v_mov_b32_e32 v134, v129
	v_mov_b64_e32 v[128:129], s[18:19]
	v_mad_i64_i32 v[128:129], s[0:1], v131, s74, v[128:129]
	v_lshl_add_u64 v[132:133], v[192:193], 1, v[128:129]
	v_pk_mul_f32 v[130:131], v[110:111], v[134:135] op_sel_hi:[1,0]
	v_pk_mul_f32 v[128:129], v[108:109], v[134:135] op_sel_hi:[1,0]
	v_pk_mul_f32 v[136:137], v[106:107], v[134:135] op_sel_hi:[1,0]
	v_pk_mul_f32 v[142:143], v[104:105], v[134:135] op_sel_hi:[1,0]
	v_cvt_pk_bf16_f32 v128, v128, v129
	v_cvt_pk_bf16_f32 v129, v130, v131
	v_cvt_pk_bf16_f32 v130, v142, v143
	v_cvt_pk_bf16_f32 v131, v136, v137
	s_and_b64 vcc, exec, s[10:11]
	s_mov_b64 s[0:1], -1
	s_cbranch_vccnz .LBB0_315
	s_mov_b64 s[0:1], 0
	global_store_dwordx4 v[132:133], v[128:131], off nt
.LBB0_315:
	s_andn2_b64 vcc, exec, s[0:1]
	v_lshl_add_u64 v[136:137], v[222:223], 0, s[14:15]
	s_cbranch_vccnz .LBB0_317
	global_store_dwordx2 v[136:137], v[128:129], off nt
	global_store_dwordx2 v[136:137], v[130:131], off offset:256 nt
.LBB0_317:
	v_mov_b32_e32 v135, v134
	v_mov_b32_e32 v128, v134
	v_mov_b32_e32 v129, v134
	v_pk_mul_f32 v[130:131], v[102:103], v[128:129]
	v_pk_mul_f32 v[142:143], v[100:101], v[134:135]
	v_pk_mul_f32 v[144:145], v[98:99], v[128:129]
	v_pk_mul_f32 v[134:135], v[96:97], v[134:135]
	v_cvt_pk_bf16_f32 v128, v142, v143
	v_cvt_pk_bf16_f32 v129, v130, v131
	v_cvt_pk_bf16_f32 v130, v134, v135
	v_cvt_pk_bf16_f32 v131, v144, v145
	s_and_b64 vcc, exec, s[10:11]
	s_mov_b64 s[0:1], -1
	s_cbranch_vccnz .LBB0_319
	s_mov_b64 s[0:1], 0
	global_store_dwordx4 v[132:133], v[128:131], off offset:256 nt

; #define LAS __attribute__((address_space(3)))
; __device__ __forceinline__ unsigned pk2(float lo, float hi) { f32x2 f = {lo, hi}; bf16x2_t b = __builtin_convertvector(f, bf16x2_t); return __builtin_bit_cast(unsigned, b); }
; __device__ __forceinline__ float row_rstd(const LAS float* RS, int ord, int lrow) {
;     const float ssum = RS[ord * 256 + lrow] + RS[2048 + ord * 256 + lrow];
;     return 1.0f / sqrtf(ssum * (1.0f / D) + 1e-6f);
; }
;     __device__ __forceinline__ void operator()(const AccT& acc, const Unit& u, int wr, int wc, int fr, int fq) const {
;     ...
;         if (!rot) {
; #pragma unroll
;             for (int ai = 0; ai < 2; ++ai)
; #pragma unroll
;                 for (int m = 0; m < 4; ++m) {
;                     const int row = row0 + ai * 128 + m * 16;
;                     const float rstd = row_rstd(RS, u.ord, wr * 64 + fr + ai * 128 + m * 16);
;                     bf16_t* rowp = P + (size_t)row * INW + col0;
; #pragma unroll
;                     for (int bj = 0; bj < 2; ++bj) {
;                         const f32x4 v0 = acc[ai][bj][m][0] * rstd, v1 = acc[ai][bj][m][1] * rstd;
;                         u32x4 w; w.x = pk2(v0[0], v0[1]); w.y = pk2(v0[2], v0[3]); w.z = pk2(v1[0], v1[1]); w.w = pk2(v1[2], v1[3]);
;                         if (isgr) {
;                             const int sp = row & (S - 1), tl = sp & 127;
;                             bf16_t* gb = GRL + ((size_t)(((row >> 12) * 8 + (pn - 28)) * 32 + (sp >> 7))) * 32768
;                                        + (size_t)((((((bj * 4 + wc) * 4 + fq) * 4 + (tl >> 5)) * 2) * 32 + (tl & 31)) * 4);
;                             u32x2 lo2; lo2.x = w.x; lo2.y = w.y; u32x2 hi2; hi2.x = w.z; hi2.y = w.w;
;                             *(u32x2*)gb = lo2; *(u32x2*)(gb + 32 * 4) = hi2;
;                         } else *(u32x4*)(rowp + bj * 128) = w;
;                     }
;                 }
.LBB0_321:
	v_add_u32_e32 v141, 0x80, v138
	ds_read2st64_b32 v[128:129], v141 offset1:32
	v_or_b32_e32 v135, 32, v227
	s_waitcnt lgkmcnt(0)
	v_add_f32_e32 v128, v128, v129
	v_fmamk_f32 v128, v128, 0x3a000000, v236
	v_mul_f32_e32 v129, 0x4f800000, v128
	v_cmp_gt_f32_e32 vcc, s73, v128
	s_nop 1
	v_cndmask_b32_e32 v128, v128, v129, vcc
	v_rsq_f32_e32 v129, v128
	s_nop 0
	s_nop 0
	s_nop 1
	s_nop 1
	s_nop 1
	v_mov_b32_e32 v134, v129
	v_mov_b64_e32 v[128:129], s[18:19]
	v_mad_i64_i32 v[128:129], s[0:1], v135, s74, v[128:129]
	v_lshl_add_u64 v[132:133], v[192:193], 1, v[128:129]
	v_pk_mul_f32 v[130:131], v[94:95], v[134:135] op_sel_hi:[1,0]
	v_pk_mul_f32 v[128:129], v[92:93], v[134:135] op_sel_hi:[1,0]
	v_pk_mul_f32 v[136:137], v[90:91], v[134:135] op_sel_hi:[1,0]
	v_pk_mul_f32 v[142:143], v[88:89], v[134:135] op_sel_hi:[1,0]
	v_cvt_pk_bf16_f32 v128, v128, v129
	v_cvt_pk_bf16_f32 v129, v130, v131
	v_cvt_pk_bf16_f32 v130, v142, v143
	v_cvt_pk_bf16_f32 v131, v136, v137
	s_and_b64 vcc, exec, s[10:11]
	s_mov_b64 s[0:1], -1
	s_cbranch_vccnz .LBB0_323
	s_mov_b64 s[0:1], 0
	global_store_dwordx4 v[132:133], v[128:131], off nt
.LBB0_323:
	v_lshlrev_b32_e32 v135, 1, v135
	v_and_or_b32 v135, v135, s86, v228
	s_andn2_b64 vcc, exec, s[0:1]
	v_lshl_or_b32 v136, v135, 3, v232
	s_cbranch_vccnz .LBB0_325
	s_add_u32 s0, s20, s14
	s_addc_u32 s1, s21, s15
	global_store_dwordx2 v136, v[128:129], s[0:1] nt
	global_store_dwordx2 v136, v[130:131], s[0:1] offset:256 nt
.LBB0_325:
	v_mov_b32_e32 v135, v134
	v_mov_b32_e32 v128, v134
	v_mov_b32_e32 v129, v134
	v_pk_mul_f32 v[130:131], v[86:87], v[128:129]
	v_pk_mul_f32 v[142:143], v[84:85], v[134:135]
	v_pk_mul_f32 v[144:145], v[82:83], v[128:129]
	v_pk_mul_f32 v[134:135], v[80:81], v[134:135]
	v_cvt_pk_bf16_f32 v128, v142, v143
	v_cvt_pk_bf16_f32 v129, v130, v131
	v_cvt_pk_bf16_f32 v130, v134, v135
	v_cvt_pk_bf16_f32 v131, v144, v145
	s_and_b64 vcc, exec, s[10:11]
	s_mov_b64 s[0:1], -1
	s_cbranch_vccnz .LBB0_327
	s_mov_b64 s[0:1], 0
	global_store_dwordx4 v[132:133], v[128:131], off offset:256 nt
.LBB0_327:
	s_andn2_b64 vcc, exec, s[0:1]
	s_cbranch_vccnz .LBB0_329
	s_add_u32 s0, s20, s14
	s_addc_u32 s1, s21, s15
	v_mov_b32_e32 v137, v193
	v_lshl_add_u64 v[132:133], s[0:1], 0, v[136:137]
	v_add_co_u32_e32 v132, vcc, 0x8000, v132
	s_nop 1
	v_addc_co_u32_e32 v133, vcc, 0, v133, vcc
	global_store_dwordx2 v[132:133], v[128:129], off nt
	global_store_dwordx2 v[132:133], v[130:131], off offset:256 nt
.LBB0_329:
	v_add_u32_e32 v142, 0xc0, v138
	ds_read2st64_b32 v[128:129], v142 offset1:32
	v_or_b32_e32 v135, 48, v227
	s_waitcnt lgkmcnt(0)
	v_add_f32_e32 v128, v128, v129
	v_fmamk_f32 v128, v128, 0x3a000000, v236
	v_mul_f32_e32 v129, 0x4f800000, v128
	v_cmp_gt_f32_e32 vcc, s73, v128
	s_nop 1
	v_cndmask_b32_e32 v128, v128, v129, vcc
	v_rsq_f32_e32 v129, v128
	s_nop 0
	s_nop 0
	s_nop 1
	s_nop 1
	s_nop 1
	v_mov_b32_e32 v134, v129
	v_mov_b64_e32 v[128:129], s[18:19]
	v_mad_i64_i32 v[128:129], s[0:1], v135, s74, v[128:129]
	v_lshl_add_u64 v[132:133], v[192:193], 1, v[128:129]
	v_pk_mul_f32 v[130:131], v[78:79], v[134:135] op_sel_hi:[1,0]
	v_pk_mul_f32 v[128:129], v[76:77], v[134:135] op_sel_hi:[1,0]
	v_pk_mul_f32 v[136:137], v[74:75], v[134:135] op_sel_hi:[1,0]
	v_pk_mul_f32 v[144:145], v[72:73], v[134:135] op_sel_hi:[1,0]
	v_cvt_pk_bf16_f32 v128, v128, v129
	v_cvt_pk_bf16_f32 v129, v130, v131
	v_cvt_pk_bf16_f32 v130, v144, v145
	v_cvt_pk_bf16_f32 v131, v136, v137
	s_and_b64 vcc, exec, s[10:11]
	s_mov_b64 s[0:1], -1
	s_cbranch_vccnz .LBB0_331
	s_mov_b64 s[0:1], 0
	global_store_dwordx4 v[132:133], v[128:131], off nt
.LBB0_331:
	v_lshlrev_b32_e32 v135, 1, v135
	v_and_or_b32 v135, v135, s86, v231
	s_andn2_b64 vcc, exec, s[0:1]
	v_lshl_or_b32 v136, v135, 3, v232
	s_cbranch_vccnz .LBB0_333
	s_add_u32 s0, s20, s14
	s_addc_u32 s1, s21, s15
	global_store_dwordx2 v136, v[128:129], s[0:1] nt
	global_store_dwordx2 v136, v[130:131], s[0:1] offset:256 nt
.LBB0_333:
	v_mov_b32_e32 v135, v134
	v_mov_b32_e32 v128, v134
	v_mov_b32_e32 v129, v134
	v_pk_mul_f32 v[130:131], v[70:71], v[128:129]
	v_pk_mul_f32 v[144:145], v[68:69], v[134:135]
	v_pk_mul_f32 v[146:147], v[66:67], v[128:129]
	v_pk_mul_f32 v[134:135], v[64:65], v[134:135]
	v_cvt_pk_bf16_f32 v128, v144, v145
	v_cvt_pk_bf16_f32 v129, v130, v131
	v_cvt_pk_bf16_f32 v130, v134, v135
	v_cvt_pk_bf16_f32 v131, v146, v147
	s_and_b64 vcc, exec, s[10:11]
	s_mov_b64 s[0:1], -1
	s_cbranch_vccnz .LBB0_335
	s_mov_b64 s[0:1], 0
	global_store_dwordx4 v[132:133], v[128:131], off offset:256 nt

; #define LAS __attribute__((address_space(3)))
; __device__ __forceinline__ unsigned pk2(float lo, float hi) { f32x2 f = {lo, hi}; bf16x2_t b = __builtin_convertvector(f, bf16x2_t); return __builtin_bit_cast(unsigned, b); }
; __device__ __forceinline__ float row_rstd(const LAS float* RS, int ord, int lrow) {
;     const float ssum = RS[ord * 256 + lrow] + RS[2048 + ord * 256 + lrow];
;     return 1.0f / sqrtf(ssum * (1.0f / D) + 1e-6f);
; }
;     __device__ __forceinline__ void operator()(const AccT& acc, const Unit& u, int wr, int wc, int fr, int fq) const {
;     ...
;         if (!rot) {
; #pragma unroll
;             for (int ai = 0; ai < 2; ++ai)
; #pragma unroll
;                 for (int m = 0; m < 4; ++m) {
;                     const int row = row0 + ai * 128 + m * 16;
;                     const float rstd = row_rstd(RS, u.ord, wr * 64 + fr + ai * 128 + m * 16);
;                     bf16_t* rowp = P + (size_t)row * INW + col0;
; #pragma unroll
;                     for (int bj = 0; bj < 2; ++bj) {
;                         const f32x4 v0 = acc[ai][bj][m][0] * rstd, v1 = acc[ai][bj][m][1] * rstd;
;                         u32x4 w; w.x = pk2(v0[0], v0[1]); w.y = pk2(v0[2], v0[3]); w.z = pk2(v1[0], v1[1]); w.w = pk2(v1[2], v1[3]);
;                         if (isgr) {
;                             const int sp = row & (S - 1), tl = sp & 127;
;                             bf16_t* gb = GRL + ((size_t)(((row >> 12) * 8 + (pn - 28)) * 32 + (sp >> 7))) * 32768
;                                        + (size_t)((((((bj * 4 + wc) * 4 + fq) * 4 + (tl >> 5)) * 2) * 32 + (tl & 31)) * 4);
;                             u32x2 lo2; lo2.x = w.x; lo2.y = w.y; u32x2 hi2; hi2.x = w.z; hi2.y = w.w;
;                             *(u32x2*)gb = lo2; *(u32x2*)(gb + 32 * 4) = hi2;
;                         } else *(u32x4*)(rowp + bj * 128) = w;
;                     }
;                 }
.LBB0_337:
	ds_read2st64_b32 v[128:129], v138 offset0:2 offset1:34
	v_add_u32_e32 v143, 0x80, v227
	s_waitcnt lgkmcnt(0)
	v_add_f32_e32 v128, v128, v129
	v_fmamk_f32 v128, v128, 0x3a000000, v236
	v_mul_f32_e32 v129, 0x4f800000, v128
	v_cmp_gt_f32_e32 vcc, s73, v128
	s_nop 1
	v_cndmask_b32_e32 v128, v128, v129, vcc
	v_rsq_f32_e32 v129, v128
	s_nop 0
	s_nop 0
	s_nop 1
	s_nop 1
	s_nop 1
	v_mov_b32_e32 v136, v129
	v_mov_b64_e32 v[128:129], s[18:19]
	v_mad_i64_i32 v[128:129], s[0:1], v143, s74, v[128:129]
	v_lshl_add_u64 v[134:135], v[192:193], 1, v[128:129]
	v_pk_mul_f32 v[130:131], v[62:63], v[136:137] op_sel_hi:[1,0]
	v_pk_mul_f32 v[128:129], v[60:61], v[136:137] op_sel_hi:[1,0]
	v_pk_mul_f32 v[132:133], v[58:59], v[136:137] op_sel_hi:[1,0]
	v_pk_mul_f32 v[138:139], v[56:57], v[136:137] op_sel_hi:[1,0]
	v_cvt_pk_bf16_f32 v128, v128, v129
	v_cvt_pk_bf16_f32 v129, v130, v131
	v_cvt_pk_bf16_f32 v130, v138, v139
	v_cvt_pk_bf16_f32 v131, v132, v133
	s_and_b64 vcc, exec, s[10:11]
	s_mov_b64 s[0:1], -1
	s_cbranch_vccnz .LBB0_339
	s_mov_b64 s[0:1], 0
	global_store_dwordx4 v[134:135], v[128:131], off nt
.LBB0_339:
	v_ashrrev_i32_e32 v132, 9, v143
	v_and_b32_e32 v132, 0x7fffff8, v132
	v_add_u32_e32 v132, s25, v132
	v_bfe_u32 v133, v143, 7, 5
	v_lshl_or_b32 v132, v132, 5, v133
	v_ashrrev_i32_e32 v133, 31, v132
	v_lshlrev_b64 v[132:133], 16, v[132:133]
	s_andn2_b64 vcc, exec, s[0:1]
	v_lshl_add_u64 v[138:139], v[220:221], 0, v[132:133]
	s_cbranch_vccnz .LBB0_341
	global_store_dwordx2 v[138:139], v[128:129], off nt
	global_store_dwordx2 v[138:139], v[130:131], off offset:256 nt
.LBB0_341:
	v_mov_b32_e32 v137, v136
	v_mov_b32_e32 v128, v136
	v_mov_b32_e32 v129, v136
	v_pk_mul_f32 v[130:131], v[54:55], v[128:129]
	v_pk_mul_f32 v[144:145], v[52:53], v[136:137]
	v_pk_mul_f32 v[146:147], v[50:51], v[128:129]
	v_pk_mul_f32 v[136:137], v[48:49], v[136:137]
	v_cvt_pk_bf16_f32 v128, v144, v145
	v_cvt_pk_bf16_f32 v129, v130, v131
	v_cvt_pk_bf16_f32 v130, v136, v137
	v_cvt_pk_bf16_f32 v131, v146, v147
	s_and_b64 vcc, exec, s[10:11]
	s_mov_b64 s[0:1], -1
	s_cbranch_vccnz .LBB0_343
	s_mov_b64 s[0:1], 0
	global_store_dwordx4 v[134:135], v[128:131], off offset:256 nt
.LBB0_343:
	s_andn2_b64 vcc, exec, s[0:1]
	s_cbranch_vccnz .LBB0_345
	v_add_co_u32_e32 v134, vcc, 0x8000, v138
	s_nop 1
	v_addc_co_u32_e32 v135, vcc, 0, v139, vcc
	global_store_dwordx2 v[134:135], v[128:129], off nt
	global_store_dwordx2 v[134:135], v[130:131], off offset:256 nt
.LBB0_345:
	ds_read2st64_b32 v[128:129], v140 offset0:2 offset1:34
	s_waitcnt lgkmcnt(0)
	v_add_f32_e32 v128, v128, v129
	v_fmamk_f32 v128, v128, 0x3a000000, v236
	v_mul_f32_e32 v129, 0x4f800000, v128
	v_cmp_gt_f32_e32 vcc, s73, v128
	s_nop 1
	v_cndmask_b32_e32 v128, v128, v129, vcc
	v_rsq_f32_e32 v129, v128
	s_nop 0
	s_nop 0
	s_nop 1
	s_nop 1
	v_or_b32_e32 v131, 16, v143
	s_nop 0
	v_mov_b32_e32 v136, v129
	v_mov_b64_e32 v[128:129], s[18:19]
	v_mad_i64_i32 v[128:129], s[0:1], v131, s74, v[128:129]
	v_lshl_add_u64 v[134:135], v[192:193], 1, v[128:129]
	v_pk_mul_f32 v[130:131], v[46:47], v[136:137] op_sel_hi:[1,0]
	v_pk_mul_f32 v[128:129], v[44:45], v[136:137] op_sel_hi:[1,0]
	v_pk_mul_f32 v[138:139], v[42:43], v[136:137] op_sel_hi:[1,0]
	v_pk_mul_f32 v[144:145], v[40:41], v[136:137] op_sel_hi:[1,0]
	v_cvt_pk_bf16_f32 v128, v128, v129
	v_cvt_pk_bf16_f32 v129, v130, v131
	v_cvt_pk_bf16_f32 v130, v144, v145
	v_cvt_pk_bf16_f32 v131, v138, v139
	s_and_b64 vcc, exec, s[10:11]
	s_mov_b64 s[0:1], -1
	s_cbranch_vccnz .LBB0_347
	s_mov_b64 s[0:1], 0
	global_store_dwordx4 v[134:135], v[128:131], off nt
.LBB0_347:
	s_andn2_b64 vcc, exec, s[0:1]
	v_lshl_add_u64 v[138:139], v[222:223], 0, v[132:133]
	s_cbranch_vccnz .LBB0_349
	global_store_dwordx2 v[138:139], v[128:129], off nt
	global_store_dwordx2 v[138:139], v[130:131], off offset:256 nt
.LBB0_349:
	v_mov_b32_e32 v137, v136
	v_mov_b32_e32 v128, v136
	v_mov_b32_e32 v129, v136
	v_pk_mul_f32 v[130:131], v[38:39], v[128:129]
	v_pk_mul_f32 v[144:145], v[36:37], v[136:137]
	v_pk_mul_f32 v[146:147], v[34:35], v[128:129]
	v_pk_mul_f32 v[136:137], v[32:33], v[136:137]
	v_cvt_pk_bf16_f32 v128, v144, v145
	v_cvt_pk_bf16_f32 v129, v130, v131
	v_cvt_pk_bf16_f32 v130, v136, v137
	v_cvt_pk_bf16_f32 v131, v146, v147
	s_and_b64 vcc, exec, s[10:11]
	s_mov_b64 s[0:1], -1
	s_cbranch_vccnz .LBB0_351
	s_mov_b64 s[0:1], 0
	global_store_dwordx4 v[134:135], v[128:131], off offset:256 nt

; #define LAS __attribute__((address_space(3)))
; __device__ __forceinline__ unsigned pk2(float lo, float hi) { f32x2 f = {lo, hi}; bf16x2_t b = __builtin_convertvector(f, bf16x2_t); return __builtin_bit_cast(unsigned, b); }
; __device__ __forceinline__ float row_rstd(const LAS float* RS, int ord, int lrow) {
;     const float ssum = RS[ord * 256 + lrow] + RS[2048 + ord * 256 + lrow];
;     return 1.0f / sqrtf(ssum * (1.0f / D) + 1e-6f);
; }
;     __device__ __forceinline__ void operator()(const AccT& acc, const Unit& u, int wr, int wc, int fr, int fq) const {
;     ...
;         if (!rot) {
; #pragma unroll
;             for (int ai = 0; ai < 2; ++ai)
; #pragma unroll
;                 for (int m = 0; m < 4; ++m) {
;                     const int row = row0 + ai * 128 + m * 16;
;                     const float rstd = row_rstd(RS, u.ord, wr * 64 + fr + ai * 128 + m * 16);
;                     bf16_t* rowp = P + (size_t)row * INW + col0;
; #pragma unroll
;                     for (int bj = 0; bj < 2; ++bj) {
;                         const f32x4 v0 = acc[ai][bj][m][0] * rstd, v1 = acc[ai][bj][m][1] * rstd;
;                         u32x4 w; w.x = pk2(v0[0], v0[1]); w.y = pk2(v0[2], v0[3]); w.z = pk2(v1[0], v1[1]); w.w = pk2(v1[2], v1[3]);
;                         if (isgr) {
;                             const int sp = row & (S - 1), tl = sp & 127;
;                             bf16_t* gb = GRL + ((size_t)(((row >> 12) * 8 + (pn - 28)) * 32 + (sp >> 7))) * 32768
;                                        + (size_t)((((((bj * 4 + wc) * 4 + fq) * 4 + (tl >> 5)) * 2) * 32 + (tl & 31)) * 4);
;                             u32x2 lo2; lo2.x = w.x; lo2.y = w.y; u32x2 hi2; hi2.x = w.z; hi2.y = w.w;
;                             *(u32x2*)gb = lo2; *(u32x2*)(gb + 32 * 4) = hi2;
;                         } else *(u32x4*)(rowp + bj * 128) = w;
;                     }
;                 }
.LBB0_353:
	ds_read2st64_b32 v[128:129], v141 offset0:2 offset1:34
	v_or_b32_e32 v137, 32, v143
	s_waitcnt lgkmcnt(0)
	v_add_f32_e32 v128, v128, v129
	v_fmamk_f32 v128, v128, 0x3a000000, v236
	v_mul_f32_e32 v129, 0x4f800000, v128
	v_cmp_gt_f32_e32 vcc, s73, v128
	s_nop 1
	v_cndmask_b32_e32 v128, v128, v129, vcc
	v_rsq_f32_e32 v129, v128
	s_nop 0
	s_nop 0
	s_nop 1
	s_nop 1
	s_nop 1
	v_mov_b32_e32 v136, v129
	v_mov_b64_e32 v[128:129], s[18:19]
	v_mad_i64_i32 v[128:129], s[0:1], v137, s74, v[128:129]
	v_lshl_add_u64 v[134:135], v[192:193], 1, v[128:129]
	v_pk_mul_f32 v[130:131], v[30:31], v[136:137] op_sel_hi:[1,0]
	v_pk_mul_f32 v[128:129], v[28:29], v[136:137] op_sel_hi:[1,0]
	v_pk_mul_f32 v[138:139], v[26:27], v[136:137] op_sel_hi:[1,0]
	v_pk_mul_f32 v[140:141], v[24:25], v[136:137] op_sel_hi:[1,0]
	v_cvt_pk_bf16_f32 v128, v128, v129
	v_cvt_pk_bf16_f32 v129, v130, v131
	v_cvt_pk_bf16_f32 v130, v140, v141
	v_cvt_pk_bf16_f32 v131, v138, v139
	s_and_b64 vcc, exec, s[10:11]
	s_mov_b64 s[0:1], -1
	s_cbranch_vccnz .LBB0_355
	s_mov_b64 s[0:1], 0
	global_store_dwordx4 v[134:135], v[128:131], off nt
.LBB0_355:
	v_lshlrev_b32_e32 v137, 1, v137
	v_and_or_b32 v137, v137, s86, v228
	s_andn2_b64 vcc, exec, s[0:1]
	v_lshl_add_u64 v[132:133], s[20:21], 0, v[132:133]
	v_lshl_or_b32 v138, v137, 3, v232
	s_cbranch_vccnz .LBB0_357
	v_mov_b32_e32 v139, v193
	v_lshl_add_u64 v[140:141], v[132:133], 0, v[138:139]
	global_store_dwordx2 v[140:141], v[128:129], off nt
	global_store_dwordx2 v[140:141], v[130:131], off offset:256 nt
.LBB0_357:
	v_mov_b32_e32 v137, v136
	v_mov_b32_e32 v128, v136
	v_mov_b32_e32 v129, v136
	v_pk_mul_f32 v[130:131], v[22:23], v[128:129]
	v_pk_mul_f32 v[140:141], v[20:21], v[136:137]
	v_pk_mul_f32 v[144:145], v[18:19], v[128:129]
	v_pk_mul_f32 v[136:137], v[16:17], v[136:137]
	v_cvt_pk_bf16_f32 v128, v140, v141
	v_cvt_pk_bf16_f32 v129, v130, v131
	v_cvt_pk_bf16_f32 v130, v136, v137
	v_cvt_pk_bf16_f32 v131, v144, v145
	s_and_b64 vcc, exec, s[10:11]
	s_mov_b64 s[0:1], -1
	s_cbranch_vccnz .LBB0_359
	s_mov_b64 s[0:1], 0
	global_store_dwordx4 v[134:135], v[128:131], off offset:256 nt
.LBB0_359:
	s_andn2_b64 vcc, exec, s[0:1]
	s_cbranch_vccnz .LBB0_361
	v_mov_b32_e32 v139, v193
	v_lshl_add_u64 v[134:135], v[132:133], 0, v[138:139]
	v_add_co_u32_e32 v134, vcc, 0x8000, v134
	s_nop 1
	v_addc_co_u32_e32 v135, vcc, 0, v135, vcc
	global_store_dwordx2 v[134:135], v[128:129], off nt
	global_store_dwordx2 v[134:135], v[130:131], off offset:256 nt
.LBB0_361:
	ds_read2st64_b32 v[128:129], v142 offset0:2 offset1:34
	v_or_b32_e32 v137, 48, v143
	s_waitcnt lgkmcnt(0)
	v_add_f32_e32 v128, v128, v129
	v_fmamk_f32 v128, v128, 0x3a000000, v236
	v_mul_f32_e32 v129, 0x4f800000, v128
	v_cmp_gt_f32_e32 vcc, s73, v128
	s_nop 1
	v_cndmask_b32_e32 v128, v128, v129, vcc
	v_rsq_f32_e32 v129, v128
	s_nop 0
	s_nop 0
	s_nop 1
	s_nop 1
	s_nop 1
	v_mov_b32_e32 v136, v129
	v_mov_b64_e32 v[128:129], s[18:19]
	v_mad_i64_i32 v[128:129], s[0:1], v137, s74, v[128:129]
	v_lshl_add_u64 v[134:135], v[192:193], 1, v[128:129]
	v_pk_mul_f32 v[130:131], v[14:15], v[136:137] op_sel_hi:[1,0]
	v_pk_mul_f32 v[128:129], v[12:13], v[136:137] op_sel_hi:[1,0]
	v_pk_mul_f32 v[138:139], v[10:11], v[136:137] op_sel_hi:[1,0]
	v_pk_mul_f32 v[140:141], v[8:9], v[136:137] op_sel_hi:[1,0]
	v_cvt_pk_bf16_f32 v128, v128, v129
	v_cvt_pk_bf16_f32 v129, v130, v131
	v_cvt_pk_bf16_f32 v130, v140, v141
	v_cvt_pk_bf16_f32 v131, v138, v139
	s_and_b64 vcc, exec, s[10:11]
	s_mov_b64 s[0:1], -1
	s_cbranch_vccnz .LBB0_363
	s_mov_b64 s[0:1], 0
	global_store_dwordx4 v[134:135], v[128:131], off nt
.LBB0_363:
	v_lshlrev_b32_e32 v137, 1, v137
	v_and_or_b32 v137, v137, s86, v231
	s_andn2_b64 vcc, exec, s[0:1]
	v_lshl_or_b32 v138, v137, 3, v232
	s_cbranch_vccnz .LBB0_365
	v_mov_b32_e32 v139, v193
	v_lshl_add_u64 v[140:141], v[132:133], 0, v[138:139]
	global_store_dwordx2 v[140:141], v[128:129], off nt
	global_store_dwordx2 v[140:141], v[130:131], off offset:256 nt
.LBB0_365:
	v_mov_b32_e32 v137, v136
	v_mov_b32_e32 v128, v136
	v_mov_b32_e32 v129, v136
	v_pk_mul_f32 v[130:131], v[6:7], v[128:129]
	v_pk_mul_f32 v[140:141], v[4:5], v[136:137]
	v_pk_mul_f32 v[142:143], v[2:3], v[128:129]
	v_pk_mul_f32 v[136:137], v[0:1], v[136:137]
	v_cvt_pk_bf16_f32 v128, v140, v141
	v_cvt_pk_bf16_f32 v129, v130, v131
	v_cvt_pk_bf16_f32 v130, v136, v137
	v_cvt_pk_bf16_f32 v131, v142, v143
	s_and_b64 vcc, exec, s[10:11]
	s_mov_b64 s[0:1], -1
	s_cbranch_vccnz .LBB0_367
	s_mov_b64 s[0:1], 0
	global_store_dwordx4 v[134:135], v[128:131], off offset:256 nt
.LBB0_367:
	s_andn2_b64 vcc, exec, s[0:1]
	s_cbranch_vccnz .LBB0_369
	v_mov_b32_e32 v139, v193
	v_lshl_add_u64 v[132:133], v[132:133], 0, v[138:139]
	v_add_co_u32_e32 v132, vcc, 0x8000, v132
	s_nop 1
	v_addc_co_u32_e32 v133, vcc, 0, v133, vcc
	global_store_dwordx2 v[132:133], v[128:129], off nt
	global_store_dwordx2 v[132:133], v[130:131], off offset:256 nt

; __device__ __forceinline__ unsigned pk2(float lo, float hi) { f32x2 f = {lo, hi}; bf16x2_t b = __builtin_convertvector(f, bf16x2_t); return __builtin_bit_cast(unsigned, b); }
;     __device__ __forceinline__ void operator()(const AccT& acc, const Unit& u, int wr, int wc, int fr, int fq) const {
;     ...
;         const bool kindr = pn >= 12;
;         const float* ctab = rope + (kindr ? 2 : 0) * (4096 * 64);
;         const float* stab = ctab + 4096 * 64;
;         const float sc = (pn >= 16 && pn < 20) ? 0.08838834764831845f : 1.0f;
;         const bool kmean = (pn >= 4 && pn < 8);
;         f32x4 cs[2][2];
; #pragma unroll
;         for (int bj = 0; bj < 2; ++bj)
; #pragma unroll
;             for (int n = 0; n < 2; ++n) cs[bj][n] = (f32x4){0.f, 0.f, 0.f, 0.f};
;         f32x4 cv[2][4], sv[2][4];
; #pragma unroll
;         for (int ai = 0; ai < 2; ++ai)
; #pragma unroll
;             for (int m = 0; m < 4; ++m) {
;                 const int pos = (row0 + ai * 128 + m * 16) & (S - 1);
;                 cv[ai][m] = *(const f32x4*)(ctab + pos * 64 + wc * 16 + fq * 4);
;                 sv[ai][m] = *(const f32x4*)(stab + pos * 64 + wc * 16 + fq * 4);
;             }
;         __builtin_amdgcn_sched_barrier(0);
; #pragma unroll
;         for (int ai = 0; ai < 2; ++ai)
; #pragma unroll
;             for (int m = 0; m < 4; ++m) {
;                 const int row = row0 + ai * 128 + m * 16;
;                 const float rs = sc * row_rstd(RS, u.ord, wr * 64 + fr + ai * 128 + m * 16);
;                 const f32x4 c4 = cv[ai][m] * rs;
;                 const f32x4 s4 = sv[ai][m] * rs;
;                 bf16_t* rowp = P + (size_t)row * INW + col0;
; #pragma unroll
;                 for (int bj = 0; bj < 2; ++bj) {
;                     const f32x4 x1 = acc[ai][bj][m][0], x2 = acc[ai][bj][m][1];
;                     const f32x4 o1 = x1 * c4 - x2 * s4, o2 = x1 * s4 + x2 * c4;
;                     cs[bj][0] += o1; cs[bj][1] += o2;
;                     u32x4 w; w.x = pk2(o1[0], o1[1]); w.y = pk2(o1[2], o1[3]); w.z = pk2(o2[0], o2[1]); w.w = pk2(o2[2], o2[3]);
;                     *(u32x4*)(rowp + bj * 128) = w;
;                 }
;             }
.LBB0_370:
	s_cmp_gt_i32 s92, 11
	s_cselect_b32 s0, 0x200000, 0
	s_add_u32 s0, s45, s0
	s_addc_u32 s1, s52, 0
	s_and_b32 s10, s92, -4
	s_cmp_eq_u32 s10, 16
	s_cselect_b64 vcc, -1, 0
	s_add_u32 s0, s0, s59
	s_addc_u32 s1, s1, 0
	v_mov_b32_e32 v225, v193
	v_lshlrev_b32_e32 v132, 8, v227
	v_lshl_add_u64 v[128:129], s[0:1], 0, v[224:225]
	s_mov_b64 s[0:1], 0x100000
	v_and_b32_e32 v132, 0xfcf00, v132
	v_mov_b32_e32 v133, v193
	v_lshl_add_u64 v[130:131], v[128:129], 0, s[0:1]
	v_lshl_add_u64 v[134:135], v[128:129], 0, v[132:133]
	v_lshl_add_u64 v[136:137], v[130:131], 0, v[132:133]
	global_load_dwordx4 v[188:191], v[134:135], off
	global_load_dwordx4 v[184:187], v[136:137], off
	v_or_b32_e32 v134, 0x1000, v132
	v_mov_b32_e32 v135, v193
	v_lshl_add_u64 v[136:137], v[128:129], 0, v[134:135]
	v_lshl_add_u64 v[134:135], v[130:131], 0, v[134:135]
	global_load_dwordx4 v[180:183], v[136:137], off
	global_load_dwordx4 v[176:179], v[134:135], off
	v_or_b32_e32 v134, 0x2000, v132
	v_mov_b32_e32 v135, v193
	v_lshl_add_u64 v[136:137], v[128:129], 0, v[134:135]
	v_lshl_add_u64 v[134:135], v[130:131], 0, v[134:135]
	v_or_b32_e32 v132, 0x3000, v132
	global_load_dwordx4 v[172:175], v[136:137], off
	global_load_dwordx4 v[168:171], v[134:135], off
	v_lshl_add_u64 v[134:135], v[128:129], 0, v[132:133]
	v_lshl_add_u64 v[132:133], v[130:131], 0, v[132:133]
	global_load_dwordx4 v[164:167], v[134:135], off
	global_load_dwordx4 v[160:163], v[132:133], off
	v_mov_b32_e32 v132, 0x2000
	v_lshl_add_u32 v132, v227, 6, v132
	v_and_b32_e32 v132, 0x3f3c0, v132
	v_lshlrev_b32_e32 v132, 2, v132
	v_mov_b32_e32 v133, v193
	v_lshl_add_u64 v[134:135], v[128:129], 0, v[132:133]
	v_lshl_add_u64 v[136:137], v[130:131], 0, v[132:133]
	global_load_dwordx4 v[156:159], v[134:135], off
	global_load_dwordx4 v[152:155], v[136:137], off
	v_or_b32_e32 v134, 0x1000, v132
	v_mov_b32_e32 v135, v193
	v_lshl_add_u64 v[136:137], v[128:129], 0, v[134:135]
	v_lshl_add_u64 v[134:135], v[130:131], 0, v[134:135]
	global_load_dwordx4 v[148:151], v[136:137], off
	global_load_dwordx4 v[144:147], v[134:135], off
	v_or_b32_e32 v134, 0x2000, v132
	v_mov_b32_e32 v135, v193
	v_or_b32_e32 v132, 0x3000, v132
	v_lshl_add_u64 v[136:137], v[128:129], 0, v[134:135]
	v_lshl_add_u64 v[134:135], v[130:131], 0, v[134:135]
	v_lshl_add_u64 v[128:129], v[128:129], 0, v[132:133]
	v_lshl_add_u64 v[130:131], v[130:131], 0, v[132:133]
	global_load_dwordx4 v[140:143], v[136:137], off
	s_nop 0
	global_load_dwordx4 v[136:139], v[134:135], off
	s_nop 0
	global_load_dwordx4 v[132:135], v[128:129], off
	s_nop 0
	global_load_dwordx4 v[128:131], v[130:131], off
	v_mov_b32_e32 v194, 0x3db504f3
	v_cndmask_b32_e32 v225, 1.0, v194, vcc
	v_lshl_add_u32 v244, s29, 10, v233
	v_add_u32_e32 v245, 0x2000, v244
	ds_read2_b32 v[194:195], v244 offset1:16
	ds_read2_b32 v[196:197], v245 offset1:16
	s_cmp_lg_u32 s10, 4
	s_waitcnt lgkmcnt(0)
	v_add_f32_e32 v194, v194, v196
	v_fmamk_f32 v194, v194, 0x3a000000, v236
	v_mul_f32_e32 v196, 0x4f800000, v194
	v_cmp_gt_f32_e32 vcc, s73, v194
	s_nop 1
	v_cndmask_b32_e32 v194, v194, v196, vcc
	v_rsq_f32_e32 v196, v194
	s_nop 0
	s_nop 0
	v_mov_b32_e32 v202, v192
	s_nop 0
	v_ashrrev_i32_e32 v203, 31, v192
	s_nop 0
	s_nop 1
	s_nop 0
	v_mov_b32_e32 v192, v196
	v_mul_f32_e32 v192, v225, v192
	s_waitcnt vmcnt(0)
	v_pk_mul_f32 v[246:247], v[188:189], v[192:193] op_sel_hi:[1,0]
	v_mov_b64_e32 v[188:189], s[18:19]
	v_pk_mul_f32 v[248:249], v[190:191], v[192:193] op_sel_hi:[1,0]
	v_pk_mul_f32 v[250:251], v[186:187], v[192:193] op_sel_hi:[1,0]
	v_pk_mul_f32 v[252:253], v[184:185], v[192:193] op_sel_hi:[1,0]
	v_mad_i64_i32 v[184:185], s[0:1], v227, s74, v[188:189]
	v_lshlrev_b64 v[190:191], 1, v[202:203]
	v_lshl_add_u64 v[202:203], v[184:185], 0, v[190:191]
	v_pk_mul_f32 v[186:187], v[120:121], v[252:253]
	v_pk_mul_f32 v[184:185], v[122:123], v[250:251]
	v_pk_mul_f32 v[198:199], v[120:121], v[246:247]
	v_pk_mul_f32 v[120:121], v[122:123], v[248:249]
	v_pk_fma_f32 v[184:185], v[126:127], v[248:249], v[184:185] neg_lo:[0,0,1] neg_hi:[0,0,1]
	v_pk_fma_f32 v[186:187], v[124:125], v[246:247], v[186:187] neg_lo:[0,0,1] neg_hi:[0,0,1]
	v_pk_fma_f32 v[120:121], v[126:127], v[250:251], v[120:121]
	v_pk_fma_f32 v[122:123], v[124:125], v[252:253], v[198:199]
	v_cvt_pk_bf16_f32 v124, v186, v187
	v_cvt_pk_bf16_f32 v125, v184, v185
	v_cvt_pk_bf16_f32 v126, v122, v123
	v_cvt_pk_bf16_f32 v127, v120, v121
	global_store_dwordx4 v[202:203], v[124:127], off nt
	s_nop 1
	v_pk_mul_f32 v[126:127], v[112:113], v[252:253]
	v_pk_mul_f32 v[112:113], v[112:113], v[246:247]
	v_pk_fma_f32 v[126:127], v[116:117], v[246:247], v[126:127] neg_lo:[0,0,1] neg_hi:[0,0,1]
	v_pk_fma_f32 v[116:117], v[116:117], v[252:253], v[112:113]
	v_add_f32_e32 v112, v195, v197
	v_fmamk_f32 v112, v112, 0x3a000000, v236
	v_pk_mul_f32 v[124:125], v[114:115], v[250:251]
	v_pk_mul_f32 v[114:115], v[114:115], v[248:249]
	v_mul_f32_e32 v113, 0x4f800000, v112
	v_cmp_gt_f32_e32 vcc, s73, v112
	v_pk_fma_f32 v[124:125], v[118:119], v[248:249], v[124:125] neg_lo:[0,0,1] neg_hi:[0,0,1]
	v_pk_fma_f32 v[118:119], v[118:119], v[250:251], v[114:115]
	v_cndmask_b32_e32 v115, v112, v113, vcc
	v_rsq_f32_e32 v192, v115
	s_nop 0
	v_cvt_pk_bf16_f32 v112, v126, v127
	v_cvt_pk_bf16_f32 v113, v124, v125
	v_cvt_pk_bf16_f32 v114, v116, v117
	s_nop 0
	s_nop 1
	s_nop 1
	v_cvt_pk_bf16_f32 v115, v118, v119
	global_store_dwordx4 v[202:203], v[112:115], off offset:256 nt
	s_nop 1
	v_mov_b32_e32 v112, v192
	v_or_b32_e32 v113, 16, v227
	v_mul_f32_e32 v112, v225, v112
	v_pk_mul_f32 v[180:181], v[180:181], v[112:113] op_sel_hi:[1,0]
	v_pk_mul_f32 v[182:183], v[182:183], v[112:113] op_sel_hi:[1,0]
	v_pk_mul_f32 v[178:179], v[178:179], v[112:113] op_sel_hi:[1,0]
	v_pk_mul_f32 v[176:177], v[176:177], v[112:113] op_sel_hi:[1,0]
	v_mad_i64_i32 v[112:113], s[0:1], v113, s74, v[188:189]
	v_lshl_add_u64 v[194:195], v[112:113], 0, v[190:191]
	v_pk_mul_f32 v[114:115], v[104:105], v[176:177]
	v_pk_mul_f32 v[112:113], v[106:107], v[178:179]
	v_pk_mul_f32 v[196:197], v[104:105], v[180:181]
	v_pk_mul_f32 v[104:105], v[106:107], v[182:183]
	v_pk_fma_f32 v[112:113], v[110:111], v[182:183], v[112:113] neg_lo:[0,0,1] neg_hi:[0,0,1]
	v_pk_fma_f32 v[114:115], v[108:109], v[180:181], v[114:115] neg_lo:[0,0,1] neg_hi:[0,0,1]
	v_pk_fma_f32 v[104:105], v[110:111], v[178:179], v[104:105]
	v_pk_fma_f32 v[106:107], v[108:109], v[176:177], v[196:197]
	v_cvt_pk_bf16_f32 v108, v114, v115
	v_cvt_pk_bf16_f32 v109, v112, v113
	v_cvt_pk_bf16_f32 v110, v106, v107
	v_cvt_pk_bf16_f32 v111, v104, v105
	global_store_dwordx4 v[194:195], v[108:111], off nt
	ds_read2_b32 v[196:197], v244 offset0:32 offset1:48
	ds_read2_b32 v[198:199], v245 offset0:32 offset1:48
	v_pk_mul_f32 v[110:111], v[96:97], v[176:177]
	v_pk_mul_f32 v[96:97], v[96:97], v[180:181]
	v_pk_fma_f32 v[110:111], v[100:101], v[180:181], v[110:111] neg_lo:[0,0,1] neg_hi:[0,0,1]
	v_pk_fma_f32 v[100:101], v[100:101], v[176:177], v[96:97]
	s_waitcnt lgkmcnt(0)
; __device__ __forceinline__ unsigned pk2(float lo, float hi) { f32x2 f = {lo, hi}; bf16x2_t b = __builtin_convertvector(f, bf16x2_t); return __builtin_bit_cast(unsigned, b); }
;     __device__ __forceinline__ void operator()(const AccT& acc, const Unit& u, int wr, int wc, int fr, int fq) const {
;     ...
;         for (int ai = 0; ai < 2; ++ai)
; #pragma unroll
;             for (int m = 0; m < 4; ++m) {
;                 const int row = row0 + ai * 128 + m * 16;
;                 const float rs = sc * row_rstd(RS, u.ord, wr * 64 + fr + ai * 128 + m * 16);
;                 const f32x4 c4 = cv[ai][m] * rs;
;                 const f32x4 s4 = sv[ai][m] * rs;
;                 bf16_t* rowp = P + (size_t)row * INW + col0;
; #pragma unroll
;                 for (int bj = 0; bj < 2; ++bj) {
;                     const f32x4 x1 = acc[ai][bj][m][0], x2 = acc[ai][bj][m][1];
;                     const f32x4 o1 = x1 * c4 - x2 * s4, o2 = x1 * s4 + x2 * c4;
;                     cs[bj][0] += o1; cs[bj][1] += o2;
;                     u32x4 w; w.x = pk2(o1[0], o1[1]); w.y = pk2(o1[2], o1[3]); w.z = pk2(o2[0], o2[1]); w.w = pk2(o2[2], o2[3]);
;                     *(u32x4*)(rowp + bj * 128) = w;
;                 }
;             }
	v_add_f32_e32 v96, v196, v198
	v_fmamk_f32 v96, v96, 0x3a000000, v236
	v_pk_mul_f32 v[108:109], v[98:99], v[178:179]
	v_pk_mul_f32 v[98:99], v[98:99], v[182:183]
	v_mul_f32_e32 v97, 0x4f800000, v96
	v_cmp_gt_f32_e32 vcc, s73, v96
	v_pk_fma_f32 v[108:109], v[102:103], v[182:183], v[108:109] neg_lo:[0,0,1] neg_hi:[0,0,1]
	v_pk_fma_f32 v[102:103], v[102:103], v[178:179], v[98:99]
	v_cndmask_b32_e32 v99, v96, v97, vcc
	v_rsq_f32_e32 v176, v99
	s_nop 0
	v_cvt_pk_bf16_f32 v96, v110, v111
	v_cvt_pk_bf16_f32 v97, v108, v109
	v_cvt_pk_bf16_f32 v98, v100, v101
	s_nop 0
	s_nop 1
	s_nop 1
	v_cvt_pk_bf16_f32 v99, v102, v103
	global_store_dwordx4 v[194:195], v[96:99], off offset:256 nt
	s_nop 1
	v_mov_b32_e32 v96, v176
	v_or_b32_e32 v97, 32, v227
	v_mul_f32_e32 v96, v225, v96
	v_pk_mul_f32 v[172:173], v[172:173], v[96:97] op_sel_hi:[1,0]
	v_pk_mul_f32 v[174:175], v[174:175], v[96:97] op_sel_hi:[1,0]
	v_pk_mul_f32 v[170:171], v[170:171], v[96:97] op_sel_hi:[1,0]
	v_pk_mul_f32 v[168:169], v[168:169], v[96:97] op_sel_hi:[1,0]
	v_mad_i64_i32 v[96:97], s[0:1], v97, s74, v[188:189]
	v_lshl_add_u64 v[176:177], v[96:97], 0, v[190:191]
	v_pk_mul_f32 v[98:99], v[88:89], v[168:169]
	v_pk_mul_f32 v[96:97], v[90:91], v[170:171]
	v_pk_mul_f32 v[178:179], v[88:89], v[172:173]
	v_pk_mul_f32 v[88:89], v[90:91], v[174:175]
	v_pk_fma_f32 v[96:97], v[94:95], v[174:175], v[96:97] neg_lo:[0,0,1] neg_hi:[0,0,1]
	v_pk_fma_f32 v[98:99], v[92:93], v[172:173], v[98:99] neg_lo:[0,0,1] neg_hi:[0,0,1]
	v_pk_fma_f32 v[88:89], v[94:95], v[170:171], v[88:89]
	v_pk_fma_f32 v[90:91], v[92:93], v[168:169], v[178:179]
	v_cvt_pk_bf16_f32 v92, v98, v99
	v_cvt_pk_bf16_f32 v93, v96, v97
	v_cvt_pk_bf16_f32 v94, v90, v91
	v_cvt_pk_bf16_f32 v95, v88, v89
	global_store_dwordx4 v[176:177], v[92:95], off nt
	s_nop 1
	v_pk_mul_f32 v[94:95], v[80:81], v[168:169]
	v_pk_mul_f32 v[80:81], v[80:81], v[172:173]
	v_pk_fma_f32 v[94:95], v[84:85], v[172:173], v[94:95] neg_lo:[0,0,1] neg_hi:[0,0,1]
	v_pk_fma_f32 v[84:85], v[84:85], v[168:169], v[80:81]
	v_add_f32_e32 v80, v197, v199
	v_fmamk_f32 v80, v80, 0x3a000000, v236
	v_pk_mul_f32 v[92:93], v[82:83], v[170:171]
	v_pk_mul_f32 v[82:83], v[82:83], v[174:175]
	v_mul_f32_e32 v81, 0x4f800000, v80
	v_cmp_gt_f32_e32 vcc, s73, v80
	v_pk_fma_f32 v[92:93], v[86:87], v[174:175], v[92:93] neg_lo:[0,0,1] neg_hi:[0,0,1]
	v_pk_fma_f32 v[86:87], v[86:87], v[170:171], v[82:83]
	v_cndmask_b32_e32 v83, v80, v81, vcc
	v_rsq_f32_e32 v168, v83
	s_nop 0
	v_cvt_pk_bf16_f32 v80, v94, v95
	v_cvt_pk_bf16_f32 v81, v92, v93
	v_cvt_pk_bf16_f32 v82, v84, v85
	s_nop 0
	s_nop 1
	s_nop 1
	v_cvt_pk_bf16_f32 v83, v86, v87
	global_store_dwordx4 v[176:177], v[80:83], off offset:256 nt
	s_nop 1
	v_mov_b32_e32 v80, v168
	v_or_b32_e32 v81, 48, v227
	v_mul_f32_e32 v80, v225, v80
	v_pk_mul_f32 v[164:165], v[164:165], v[80:81] op_sel_hi:[1,0]
	v_pk_mul_f32 v[166:167], v[166:167], v[80:81] op_sel_hi:[1,0]
	v_pk_mul_f32 v[162:163], v[162:163], v[80:81] op_sel_hi:[1,0]
	v_pk_mul_f32 v[160:161], v[160:161], v[80:81] op_sel_hi:[1,0]
	v_mad_i64_i32 v[80:81], s[0:1], v81, s74, v[188:189]
	v_lshl_add_u64 v[168:169], v[80:81], 0, v[190:191]
	v_pk_mul_f32 v[82:83], v[72:73], v[160:161]
	v_pk_mul_f32 v[80:81], v[74:75], v[162:163]
	v_pk_mul_f32 v[170:171], v[72:73], v[164:165]
	v_pk_mul_f32 v[72:73], v[74:75], v[166:167]
	v_pk_fma_f32 v[80:81], v[78:79], v[166:167], v[80:81] neg_lo:[0,0,1] neg_hi:[0,0,1]
	v_pk_fma_f32 v[82:83], v[76:77], v[164:165], v[82:83] neg_lo:[0,0,1] neg_hi:[0,0,1]
	v_pk_fma_f32 v[72:73], v[78:79], v[162:163], v[72:73]
	v_pk_fma_f32 v[74:75], v[76:77], v[160:161], v[170:171]
	v_cvt_pk_bf16_f32 v76, v82, v83
	v_cvt_pk_bf16_f32 v77, v80, v81
	v_cvt_pk_bf16_f32 v78, v74, v75
	v_cvt_pk_bf16_f32 v79, v72, v73
	global_store_dwordx4 v[168:169], v[76:79], off nt
	ds_read2_b32 v[170:171], v244 offset0:128 offset1:144
	ds_read2_b32 v[172:173], v245 offset0:128 offset1:144
	v_pk_mul_f32 v[78:79], v[64:65], v[160:161]
	v_pk_mul_f32 v[64:65], v[64:65], v[164:165]
	v_pk_fma_f32 v[78:79], v[68:69], v[164:165], v[78:79] neg_lo:[0,0,1] neg_hi:[0,0,1]
	v_pk_fma_f32 v[68:69], v[68:69], v[160:161], v[64:65]
	s_waitcnt lgkmcnt(0)
	v_add_f32_e32 v64, v170, v172
	v_fmamk_f32 v64, v64, 0x3a000000, v236
	v_pk_mul_f32 v[76:77], v[66:67], v[162:163]
	v_pk_mul_f32 v[66:67], v[66:67], v[166:167]
	v_mul_f32_e32 v65, 0x4f800000, v64
	v_cmp_gt_f32_e32 vcc, s73, v64
	v_pk_fma_f32 v[76:77], v[70:71], v[166:167], v[76:77] neg_lo:[0,0,1] neg_hi:[0,0,1]
	v_pk_fma_f32 v[70:71], v[70:71], v[162:163], v[66:67]
	v_cndmask_b32_e32 v67, v64, v65, vcc
	v_rsq_f32_e32 v160, v67
	s_nop 0
	v_cvt_pk_bf16_f32 v64, v78, v79
	v_cvt_pk_bf16_f32 v65, v76, v77
	v_cvt_pk_bf16_f32 v66, v68, v69
	s_nop 0
	s_nop 1
	s_nop 1
	v_cvt_pk_bf16_f32 v67, v70, v71
	global_store_dwordx4 v[168:169], v[64:67], off offset:256 nt
	s_nop 1
	v_mov_b32_e32 v64, v160
	v_add_u32_e32 v65, 0x80, v227
	v_mul_f32_e32 v64, v225, v64
	v_pk_mul_f32 v[156:157], v[156:157], v[64:65] op_sel_hi:[1,0]
	v_pk_mul_f32 v[158:159], v[158:159], v[64:65] op_sel_hi:[1,0]
	v_pk_mul_f32 v[154:155], v[154:155], v[64:65] op_sel_hi:[1,0]
	v_pk_mul_f32 v[152:153], v[152:153], v[64:65] op_sel_hi:[1,0]
	v_mad_i64_i32 v[64:65], s[0:1], v65, s74, v[188:189]
	v_lshl_add_u64 v[160:161], v[64:65], 0, v[190:191]
	v_pk_mul_f32 v[66:67], v[56:57], v[152:153]
	v_pk_mul_f32 v[64:65], v[58:59], v[154:155]
	v_pk_mul_f32 v[162:163], v[56:57], v[156:157]
	v_pk_mul_f32 v[56:57], v[58:59], v[158:159]
	v_pk_fma_f32 v[64:65], v[62:63], v[158:159], v[64:65] neg_lo:[0,0,1] neg_hi:[0,0,1]
	v_pk_fma_f32 v[66:67], v[60:61], v[156:157], v[66:67] neg_lo:[0,0,1] neg_hi:[0,0,1]
	v_pk_fma_f32 v[56:57], v[62:63], v[154:155], v[56:57]
; __device__ __forceinline__ unsigned pk2(float lo, float hi) { f32x2 f = {lo, hi}; bf16x2_t b = __builtin_convertvector(f, bf16x2_t); return __builtin_bit_cast(unsigned, b); }
;     __device__ __forceinline__ void operator()(const AccT& acc, const Unit& u, int wr, int wc, int fr, int fq) const {
;     ...
;         for (int ai = 0; ai < 2; ++ai)
; #pragma unroll
;             for (int m = 0; m < 4; ++m) {
;                 const int row = row0 + ai * 128 + m * 16;
;                 const float rs = sc * row_rstd(RS, u.ord, wr * 64 + fr + ai * 128 + m * 16);
;                 const f32x4 c4 = cv[ai][m] * rs;
;                 const f32x4 s4 = sv[ai][m] * rs;
;                 bf16_t* rowp = P + (size_t)row * INW + col0;
; #pragma unroll
;                 for (int bj = 0; bj < 2; ++bj) {
;                     const f32x4 x1 = acc[ai][bj][m][0], x2 = acc[ai][bj][m][1];
;                     const f32x4 o1 = x1 * c4 - x2 * s4, o2 = x1 * s4 + x2 * c4;
;                     cs[bj][0] += o1; cs[bj][1] += o2;
;                     u32x4 w; w.x = pk2(o1[0], o1[1]); w.y = pk2(o1[2], o1[3]); w.z = pk2(o2[0], o2[1]); w.w = pk2(o2[2], o2[3]);
;                     *(u32x4*)(rowp + bj * 128) = w;
;                 }
;             }
	v_pk_fma_f32 v[58:59], v[60:61], v[152:153], v[162:163]
	v_cvt_pk_bf16_f32 v60, v66, v67
	v_cvt_pk_bf16_f32 v61, v64, v65
	v_cvt_pk_bf16_f32 v62, v58, v59
	v_cvt_pk_bf16_f32 v63, v56, v57
	global_store_dwordx4 v[160:161], v[60:63], off nt
	s_nop 1
	v_pk_mul_f32 v[62:63], v[48:49], v[152:153]
	v_pk_mul_f32 v[48:49], v[48:49], v[156:157]
	v_pk_fma_f32 v[62:63], v[52:53], v[156:157], v[62:63] neg_lo:[0,0,1] neg_hi:[0,0,1]
	v_pk_fma_f32 v[52:53], v[52:53], v[152:153], v[48:49]
	v_add_f32_e32 v48, v171, v173
	v_fmamk_f32 v48, v48, 0x3a000000, v236
	v_pk_mul_f32 v[60:61], v[50:51], v[154:155]
	v_pk_mul_f32 v[50:51], v[50:51], v[158:159]
	v_mul_f32_e32 v49, 0x4f800000, v48
	v_cmp_gt_f32_e32 vcc, s73, v48
	v_pk_fma_f32 v[60:61], v[54:55], v[158:159], v[60:61] neg_lo:[0,0,1] neg_hi:[0,0,1]
	v_pk_fma_f32 v[54:55], v[54:55], v[154:155], v[50:51]
	v_cndmask_b32_e32 v51, v48, v49, vcc
	v_rsq_f32_e32 v152, v51
	s_nop 0
	v_cvt_pk_bf16_f32 v48, v62, v63
	v_cvt_pk_bf16_f32 v49, v60, v61
	v_cvt_pk_bf16_f32 v50, v52, v53
	s_nop 0
	s_nop 1
	s_nop 1
	v_cvt_pk_bf16_f32 v51, v54, v55
	global_store_dwordx4 v[160:161], v[48:51], off offset:256 nt
	s_nop 1
	v_mov_b32_e32 v48, v152
	v_add_u32_e32 v49, 0x90, v227
	v_mul_f32_e32 v48, v225, v48
	v_pk_mul_f32 v[148:149], v[148:149], v[48:49] op_sel_hi:[1,0]
	v_pk_mul_f32 v[150:151], v[150:151], v[48:49] op_sel_hi:[1,0]
	v_pk_mul_f32 v[146:147], v[146:147], v[48:49] op_sel_hi:[1,0]
	v_pk_mul_f32 v[144:145], v[144:145], v[48:49] op_sel_hi:[1,0]
	v_mad_i64_i32 v[48:49], s[0:1], v49, s74, v[188:189]
	v_lshl_add_u64 v[152:153], v[48:49], 0, v[190:191]
	v_pk_mul_f32 v[50:51], v[40:41], v[144:145]
	v_pk_mul_f32 v[48:49], v[42:43], v[146:147]
	v_pk_mul_f32 v[154:155], v[40:41], v[148:149]
	v_pk_mul_f32 v[40:41], v[42:43], v[150:151]
	v_pk_fma_f32 v[48:49], v[46:47], v[150:151], v[48:49] neg_lo:[0,0,1] neg_hi:[0,0,1]
	v_pk_fma_f32 v[50:51], v[44:45], v[148:149], v[50:51] neg_lo:[0,0,1] neg_hi:[0,0,1]
	v_pk_fma_f32 v[40:41], v[46:47], v[146:147], v[40:41]
	v_pk_fma_f32 v[42:43], v[44:45], v[144:145], v[154:155]
	v_cvt_pk_bf16_f32 v44, v50, v51
	v_cvt_pk_bf16_f32 v45, v48, v49
	v_cvt_pk_bf16_f32 v46, v42, v43
	v_cvt_pk_bf16_f32 v47, v40, v41
	global_store_dwordx4 v[152:153], v[44:47], off nt
	ds_read2_b32 v[154:155], v244 offset0:160 offset1:176
	ds_read2_b32 v[156:157], v245 offset0:160 offset1:176
	v_pk_mul_f32 v[46:47], v[32:33], v[144:145]
	v_pk_mul_f32 v[32:33], v[32:33], v[148:149]
	v_pk_fma_f32 v[46:47], v[36:37], v[148:149], v[46:47] neg_lo:[0,0,1] neg_hi:[0,0,1]
	v_pk_fma_f32 v[36:37], v[36:37], v[144:145], v[32:33]
	s_waitcnt lgkmcnt(0)
	v_add_f32_e32 v32, v154, v156
	v_fmamk_f32 v32, v32, 0x3a000000, v236
	v_pk_mul_f32 v[44:45], v[34:35], v[146:147]
	v_pk_mul_f32 v[34:35], v[34:35], v[150:151]
	v_mul_f32_e32 v33, 0x4f800000, v32
	v_cmp_gt_f32_e32 vcc, s73, v32
	v_pk_fma_f32 v[44:45], v[38:39], v[150:151], v[44:45] neg_lo:[0,0,1] neg_hi:[0,0,1]
	v_pk_fma_f32 v[38:39], v[38:39], v[146:147], v[34:35]
	v_cndmask_b32_e32 v35, v32, v33, vcc
	v_rsq_f32_e32 v144, v35
	s_nop 0
	v_cvt_pk_bf16_f32 v32, v46, v47
	v_cvt_pk_bf16_f32 v33, v44, v45
	v_cvt_pk_bf16_f32 v34, v36, v37
	s_nop 0
	s_nop 1
	s_nop 1
	v_cvt_pk_bf16_f32 v35, v38, v39
	global_store_dwordx4 v[152:153], v[32:35], off offset:256 nt
	s_nop 1
	v_mov_b32_e32 v32, v144
	v_add_u32_e32 v33, 0xa0, v227
	v_mul_f32_e32 v32, v225, v32
	v_pk_mul_f32 v[140:141], v[140:141], v[32:33] op_sel_hi:[1,0]
	v_pk_mul_f32 v[142:143], v[142:143], v[32:33] op_sel_hi:[1,0]
	v_pk_mul_f32 v[138:139], v[138:139], v[32:33] op_sel_hi:[1,0]
	v_pk_mul_f32 v[136:137], v[136:137], v[32:33] op_sel_hi:[1,0]
	v_mad_i64_i32 v[32:33], s[0:1], v33, s74, v[188:189]
	v_lshl_add_u64 v[144:145], v[32:33], 0, v[190:191]
	v_pk_mul_f32 v[34:35], v[24:25], v[136:137]
	v_pk_mul_f32 v[32:33], v[26:27], v[138:139]
	v_pk_mul_f32 v[146:147], v[24:25], v[140:141]
	v_pk_mul_f32 v[24:25], v[26:27], v[142:143]
	v_pk_fma_f32 v[32:33], v[30:31], v[142:143], v[32:33] neg_lo:[0,0,1] neg_hi:[0,0,1]
	v_pk_fma_f32 v[34:35], v[28:29], v[140:141], v[34:35] neg_lo:[0,0,1] neg_hi:[0,0,1]
	v_pk_fma_f32 v[24:25], v[30:31], v[138:139], v[24:25]
	v_pk_fma_f32 v[26:27], v[28:29], v[136:137], v[146:147]
	v_cvt_pk_bf16_f32 v28, v34, v35
	v_cvt_pk_bf16_f32 v29, v32, v33
	v_cvt_pk_bf16_f32 v30, v26, v27
	v_cvt_pk_bf16_f32 v31, v24, v25
	global_store_dwordx4 v[144:145], v[28:31], off nt
	s_nop 1
	v_pk_mul_f32 v[30:31], v[16:17], v[136:137]
	v_pk_mul_f32 v[16:17], v[16:17], v[140:141]
	v_pk_fma_f32 v[30:31], v[20:21], v[140:141], v[30:31] neg_lo:[0,0,1] neg_hi:[0,0,1]
	v_pk_fma_f32 v[20:21], v[20:21], v[136:137], v[16:17]
	v_add_f32_e32 v16, v155, v157
	v_fmamk_f32 v16, v16, 0x3a000000, v236
	v_pk_mul_f32 v[28:29], v[18:19], v[138:139]
	v_pk_mul_f32 v[18:19], v[18:19], v[142:143]
	v_mul_f32_e32 v17, 0x4f800000, v16
	v_cmp_gt_f32_e32 vcc, s73, v16
	v_pk_fma_f32 v[28:29], v[22:23], v[142:143], v[28:29] neg_lo:[0,0,1] neg_hi:[0,0,1]
	v_pk_fma_f32 v[22:23], v[22:23], v[138:139], v[18:19]
	v_cndmask_b32_e32 v19, v16, v17, vcc
	v_rsq_f32_e32 v136, v19
	s_nop 0
	v_cvt_pk_bf16_f32 v16, v30, v31
	v_cvt_pk_bf16_f32 v17, v28, v29
	v_cvt_pk_bf16_f32 v18, v20, v21
	s_nop 0
	s_nop 1
	s_nop 1
	v_cvt_pk_bf16_f32 v19, v22, v23
	global_store_dwordx4 v[144:145], v[16:19], off offset:256 nt
	s_nop 1
	v_mov_b32_e32 v16, v136
	v_add_u32_e32 v17, 0xb0, v227
	v_mul_f32_e32 v16, v225, v16
	v_pk_mul_f32 v[132:133], v[132:133], v[16:17] op_sel_hi:[1,0]
	v_pk_mul_f32 v[134:135], v[134:135], v[16:17] op_sel_hi:[1,0]
	v_pk_mul_f32 v[130:131], v[130:131], v[16:17] op_sel_hi:[1,0]
	v_pk_mul_f32 v[128:129], v[128:129], v[16:17] op_sel_hi:[1,0]
	v_mad_i64_i32 v[16:17], s[0:1], v17, s74, v[188:189]
	v_lshl_add_u64 v[136:137], v[16:17], 0, v[190:191]
	v_pk_mul_f32 v[18:19], v[8:9], v[128:129]
	v_pk_mul_f32 v[16:17], v[10:11], v[130:131]
	v_pk_mul_f32 v[138:139], v[8:9], v[132:133]
	v_pk_mul_f32 v[8:9], v[10:11], v[134:135]
	v_pk_fma_f32 v[16:17], v[14:15], v[134:135], v[16:17] neg_lo:[0,0,1] neg_hi:[0,0,1]
	v_pk_fma_f32 v[18:19], v[12:13], v[132:133], v[18:19] neg_lo:[0,0,1] neg_hi:[0,0,1]
	v_pk_fma_f32 v[8:9], v[14:15], v[130:131], v[8:9]
	v_pk_fma_f32 v[10:11], v[12:13], v[128:129], v[138:139]
	v_cvt_pk_bf16_f32 v12, v18, v19
	v_cvt_pk_bf16_f32 v13, v16, v17
	v_cvt_pk_bf16_f32 v14, v10, v11
	v_cvt_pk_bf16_f32 v15, v8, v9
	global_store_dwordx4 v[136:137], v[12:15], off nt
	s_nop 1
	v_pk_mul_f32 v[14:15], v[0:1], v[128:129]
	v_pk_mul_f32 v[12:13], v[2:3], v[130:131]
	v_pk_fma_f32 v[14:15], v[4:5], v[132:133], v[14:15] neg_lo:[0,0,1] neg_hi:[0,0,1]
	v_pk_mul_f32 v[132:133], v[0:1], v[132:133]
	v_pk_mul_f32 v[0:1], v[2:3], v[134:135]
	v_pk_fma_f32 v[12:13], v[6:7], v[134:135], v[12:13] neg_lo:[0,0,1] neg_hi:[0,0,1]
	v_pk_fma_f32 v[0:1], v[6:7], v[130:131], v[0:1]
	v_pk_fma_f32 v[2:3], v[4:5], v[128:129], v[132:133]
	v_cvt_pk_bf16_f32 v4, v14, v15
	v_cvt_pk_bf16_f32 v5, v12, v13
	v_cvt_pk_bf16_f32 v6, v2, v3
	v_cvt_pk_bf16_f32 v7, v0, v1
	global_store_dwordx4 v[136:137], v[4:7], off offset:256 nt
	s_cbranch_scc1 .LBB0_374
; __device__ __forceinline__ unsigned pk2(float lo, float hi) { f32x2 f = {lo, hi}; bf16x2_t b = __builtin_convertvector(f, bf16x2_t); return __builtin_bit_cast(unsigned, b); }
;     __device__ __forceinline__ void operator()(const AccT& acc, const Unit& u, int wr, int wc, int fr, int fq) const {
;     ...
;                     cs[bj][0] += o1; cs[bj][1] += o2;
;                     u32x4 w; w.x = pk2(o1[0], o1[1]); w.y = pk2(o1[2], o1[3]); w.z = pk2(o2[0], o2[1]); w.w = pk2(o2[2], o2[3]);
;                     *(u32x4*)(rowp + bj * 128) = w;
;                 }
;             }
;         if (kmean) {
; #pragma unroll
;             for (int bj = 0; bj < 2; ++bj)
; #pragma unroll
;                 for (int n = 0; n < 2; ++n)
; #pragma unroll
;                     for (int e = 0; e < 4; ++e) {
;                         float v = cs[bj][n][e];
;                         v += __shfl_xor(v, 1); v += __shfl_xor(v, 2); v += __shfl_xor(v, 4); v += __shfl_xor(v, 8);
;                         cs[bj][n][e] = v;
;                     }
;             if (fr == 0) {
	s_nop 0
	v_pk_add_f32 v[4:5], v[118:119], 0 op_sel_hi:[1,0]
	v_pk_add_f32 v[6:7], v[116:117], 0 op_sel_hi:[1,0]
	v_pk_add_f32 v[4:5], v[4:5], v[102:103]
	v_pk_add_f32 v[6:7], v[6:7], v[100:101]
	v_pk_add_f32 v[4:5], v[4:5], v[86:87]
	v_pk_add_f32 v[6:7], v[6:7], v[84:85]
	v_pk_add_f32 v[4:5], v[4:5], v[70:71]
	v_pk_add_f32 v[6:7], v[6:7], v[68:69]
	v_pk_add_f32 v[4:5], v[4:5], v[54:55]
	v_pk_add_f32 v[6:7], v[6:7], v[52:53]
	v_pk_add_f32 v[4:5], v[4:5], v[38:39]
	v_pk_add_f32 v[6:7], v[6:7], v[36:37]
	v_pk_add_f32 v[4:5], v[4:5], v[22:23]
	v_pk_add_f32 v[6:7], v[6:7], v[20:21]
	v_pk_add_f32 v[0:1], v[4:5], v[0:1]
	v_pk_add_f32 v[2:3], v[6:7], v[2:3]
	v_pk_add_f32 v[4:5], v[124:125], 0 op_sel_hi:[1,0]
	v_pk_add_f32 v[6:7], v[126:127], 0 op_sel_hi:[1,0]
	v_pk_add_f32 v[4:5], v[4:5], v[108:109]
	v_pk_add_f32 v[6:7], v[6:7], v[110:111]
	v_pk_add_f32 v[4:5], v[4:5], v[92:93]
	v_pk_add_f32 v[6:7], v[6:7], v[94:95]
	v_pk_add_f32 v[4:5], v[4:5], v[76:77]
	v_pk_add_f32 v[6:7], v[6:7], v[78:79]
	v_pk_add_f32 v[4:5], v[4:5], v[60:61]
	v_pk_add_f32 v[6:7], v[6:7], v[62:63]
	v_pk_add_f32 v[4:5], v[4:5], v[44:45]
	v_pk_add_f32 v[6:7], v[6:7], v[46:47]
	v_pk_add_f32 v[4:5], v[4:5], v[28:29]
	v_pk_add_f32 v[6:7], v[6:7], v[30:31]
	v_pk_add_f32 v[20:21], v[4:5], v[12:13]
	v_pk_add_f32 v[22:23], v[6:7], v[14:15]
	v_pk_add_f32 v[4:5], v[120:121], 0 op_sel_hi:[1,0]
	v_pk_add_f32 v[6:7], v[122:123], 0 op_sel_hi:[1,0]
	v_pk_add_f32 v[4:5], v[4:5], v[104:105]
	v_pk_add_f32 v[6:7], v[6:7], v[106:107]
	v_pk_add_f32 v[4:5], v[4:5], v[88:89]
	v_pk_add_f32 v[6:7], v[6:7], v[90:91]
	v_pk_add_f32 v[4:5], v[4:5], v[72:73]
	v_pk_add_f32 v[6:7], v[6:7], v[74:75]
	v_pk_add_f32 v[4:5], v[4:5], v[56:57]
	v_pk_add_f32 v[6:7], v[6:7], v[58:59]
	v_pk_add_f32 v[4:5], v[4:5], v[40:41]
	v_pk_add_f32 v[6:7], v[6:7], v[42:43]
	v_pk_add_f32 v[4:5], v[4:5], v[24:25]
	v_pk_add_f32 v[6:7], v[6:7], v[26:27]
	v_pk_add_f32 v[12:13], v[4:5], v[8:9]
	v_pk_add_f32 v[8:9], v[6:7], v[10:11]
	v_pk_add_f32 v[6:7], v[186:187], 0 op_sel_hi:[1,0]
	v_and_b32_e32 v11, 64, v238
	v_pk_add_f32 v[6:7], v[6:7], v[114:115]
	v_pk_add_f32 v[4:5], v[184:185], 0 op_sel_hi:[1,0]
	v_pk_add_f32 v[6:7], v[6:7], v[98:99]
	v_xor_b32_e32 v10, 1, v238
	v_add_u32_e32 v14, 64, v11
	v_pk_add_f32 v[4:5], v[4:5], v[112:113]
	v_pk_add_f32 v[6:7], v[6:7], v[82:83]
	v_cmp_lt_i32_e32 vcc, v10, v14
	v_pk_add_f32 v[4:5], v[4:5], v[96:97]
	v_pk_add_f32 v[6:7], v[6:7], v[66:67]
	v_cndmask_b32_e32 v10, v238, v10, vcc
	v_pk_add_f32 v[4:5], v[4:5], v[80:81]
	v_pk_add_f32 v[6:7], v[6:7], v[50:51]
	v_lshlrev_b32_e32 v31, 2, v10
	v_xor_b32_e32 v10, 2, v238
	v_pk_add_f32 v[4:5], v[4:5], v[64:65]
	v_pk_add_f32 v[6:7], v[6:7], v[34:35]
	v_cmp_lt_i32_e32 vcc, v10, v14
	v_pk_add_f32 v[4:5], v[4:5], v[48:49]
	v_pk_add_f32 v[6:7], v[6:7], v[18:19]
	v_cndmask_b32_e32 v10, v238, v10, vcc
	v_pk_add_f32 v[4:5], v[4:5], v[32:33]
	v_lshlrev_b32_e32 v32, 2, v10
	ds_bpermute_b32 v10, v31, v6
	ds_bpermute_b32 v11, v31, v7
	v_xor_b32_e32 v15, 4, v238
	v_cmp_lt_i32_e32 vcc, v15, v14
	v_pk_add_f32 v[4:5], v[4:5], v[16:17]
	ds_bpermute_b32 v28, v31, v20
	s_waitcnt lgkmcnt(1)
	v_pk_add_f32 v[6:7], v[6:7], v[10:11]
	ds_bpermute_b32 v10, v32, v6
	ds_bpermute_b32 v11, v32, v7
	v_cndmask_b32_e32 v15, v238, v15, vcc
	v_lshlrev_b32_e32 v33, 2, v15
	v_xor_b32_e32 v15, 8, v238
	v_cmp_lt_i32_e32 vcc, v15, v14
	ds_bpermute_b32 v14, v31, v4
	s_waitcnt lgkmcnt(1)
	v_pk_add_f32 v[6:7], v[6:7], v[10:11]
	v_cndmask_b32_e32 v16, v238, v15, vcc
	ds_bpermute_b32 v15, v31, v5
	ds_bpermute_b32 v10, v33, v6
	ds_bpermute_b32 v11, v33, v7
	v_lshlrev_b32_e32 v34, 2, v16
	ds_bpermute_b32 v29, v31, v21
	s_waitcnt lgkmcnt(3)
	v_pk_add_f32 v[14:15], v[4:5], v[14:15]
	ds_bpermute_b32 v16, v32, v14
	ds_bpermute_b32 v17, v32, v15
	s_waitcnt lgkmcnt(3)
	v_pk_add_f32 v[4:5], v[6:7], v[10:11]
	ds_bpermute_b32 v10, v31, v8
	ds_bpermute_b32 v11, v31, v9
	ds_bpermute_b32 v30, v31, v0
	s_waitcnt lgkmcnt(3)
	v_pk_add_f32 v[14:15], v[14:15], v[16:17]
	ds_bpermute_b32 v16, v33, v14
	ds_bpermute_b32 v17, v33, v15
	s_waitcnt lgkmcnt(3)
	v_pk_add_f32 v[18:19], v[8:9], v[10:11]
	ds_bpermute_b32 v24, v32, v18
	ds_bpermute_b32 v25, v32, v19
	ds_bpermute_b32 v6, v34, v4
	s_waitcnt lgkmcnt(3)
	v_pk_add_f32 v[8:9], v[14:15], v[16:17]
	ds_bpermute_b32 v14, v31, v12
	ds_bpermute_b32 v15, v31, v13
	s_waitcnt lgkmcnt(3)
	v_pk_add_f32 v[16:17], v[18:19], v[24:25]
	ds_bpermute_b32 v18, v33, v16
	ds_bpermute_b32 v19, v33, v17
	ds_bpermute_b32 v7, v34, v5
	s_waitcnt lgkmcnt(3)
	v_pk_add_f32 v[24:25], v[12:13], v[14:15]
	ds_bpermute_b32 v26, v32, v24
	ds_bpermute_b32 v27, v32, v25
	s_waitcnt lgkmcnt(3)
	v_pk_add_f32 v[12:13], v[16:17], v[18:19]
	ds_bpermute_b32 v16, v31, v22
	ds_bpermute_b32 v17, v31, v23
	ds_bpermute_b32 v10, v34, v8
	s_waitcnt lgkmcnt(3)
	v_pk_add_f32 v[18:19], v[24:25], v[26:27]
	ds_bpermute_b32 v24, v33, v18
	ds_bpermute_b32 v25, v33, v19
	s_waitcnt lgkmcnt(3)
	v_pk_add_f32 v[22:23], v[22:23], v[16:17]
	ds_bpermute_b32 v26, v32, v22
	ds_bpermute_b32 v27, v32, v23
	ds_bpermute_b32 v11, v34, v9
	s_waitcnt lgkmcnt(3)
	v_pk_add_f32 v[16:17], v[18:19], v[24:25]
	ds_bpermute_b32 v14, v34, v12
	ds_bpermute_b32 v15, v34, v13
	s_waitcnt lgkmcnt(3)
	v_pk_add_f32 v[22:23], v[22:23], v[26:27]
	v_pk_add_f32 v[26:27], v[20:21], v[28:29]
	ds_bpermute_b32 v24, v33, v22
	ds_bpermute_b32 v25, v33, v23
	ds_bpermute_b32 v28, v32, v26
	ds_bpermute_b32 v29, v32, v27
	ds_bpermute_b32 v18, v34, v16
	ds_bpermute_b32 v19, v34, v17
	s_waitcnt lgkmcnt(4)
	v_pk_add_f32 v[20:21], v[22:23], v[24:25]
	ds_bpermute_b32 v22, v34, v20
	s_waitcnt lgkmcnt(3)
	v_pk_add_f32 v[24:25], v[26:27], v[28:29]
	ds_bpermute_b32 v28, v31, v2
	ds_bpermute_b32 v29, v31, v3
	ds_bpermute_b32 v31, v31, v1
	ds_bpermute_b32 v26, v33, v24
	ds_bpermute_b32 v27, v33, v25
	ds_bpermute_b32 v23, v34, v21
	s_waitcnt lgkmcnt(4)
	v_pk_add_f32 v[2:3], v[2:3], v[28:29]
	s_waitcnt lgkmcnt(3)
	v_pk_add_f32 v[28:29], v[0:1], v[30:31]
	ds_bpermute_b32 v30, v32, v28
	s_waitcnt lgkmcnt(2)
	v_pk_add_f32 v[24:25], v[24:25], v[26:27]
	ds_bpermute_b32 v26, v32, v2
	ds_bpermute_b32 v27, v32, v3
	ds_bpermute_b32 v31, v32, v29
	ds_bpermute_b32 v0, v34, v24
	ds_bpermute_b32 v1, v34, v25
	s_waitcnt lgkmcnt(3)
	v_pk_add_f32 v[2:3], v[2:3], v[26:27]
	s_waitcnt lgkmcnt(2)
	v_pk_add_f32 v[28:29], v[28:29], v[30:31]
	ds_bpermute_b32 v26, v33, v2
	ds_bpermute_b32 v27, v33, v3
	ds_bpermute_b32 v30, v33, v28
	ds_bpermute_b32 v31, v33, v29
	s_waitcnt lgkmcnt(2)
	v_pk_add_f32 v[2:3], v[2:3], v[26:27]
	ds_bpermute_b32 v26, v34, v2
	s_waitcnt lgkmcnt(1)
	v_pk_add_f32 v[28:29], v[28:29], v[30:31]
	ds_bpermute_b32 v27, v34, v3
	ds_bpermute_b32 v30, v34, v28
	ds_bpermute_b32 v31, v34, v29
	s_and_saveexec_b64 s[0:1], s[6:7]
	s_cbranch_execz .LBB0_373
;     __device__ __forceinline__ void operator()(const AccT& acc, const Unit& u, int wr, int wc, int fr, int fq) const {
;     ...
;             if (fr == 0) {
;                 float* kp = KMP + ((size_t)wr * 32 + u.pm) * 1024 + (pn - 4) * 256 + wc * 32 + 8 * fq;
; #pragma unroll
;                 for (int bj = 0; bj < 2; ++bj) { *(f32x4*)(kp + bj * 128) = cs[bj][0]; *(f32x4*)(kp + bj * 128 + 4) = cs[bj][1]; }
;             }
	s_ashr_i32 s29, s28, 31
	s_lshl_b64 s[10:11], s[28:29], 12
	s_add_u32 s14, s54, s10
	s_addc_u32 s15, s53, s11
	s_lshl_b64 s[10:11], s[90:91], 2
	s_add_u32 s10, s14, s10
	s_addc_u32 s11, s15, s11
	s_add_u32 s10, s10, s79
	s_addc_u32 s11, s11, 0
	v_mov_b32_e32 v227, v193
	v_pk_add_f32 v[6:7], v[4:5], v[6:7]
	v_lshl_add_u64 v[4:5], s[10:11], 0, v[226:227]
	s_mov_b64 s[10:11], 0x283ff000
	v_pk_add_f32 v[8:9], v[8:9], v[10:11]
	v_lshl_add_u64 v[10:11], v[4:5], 0, s[10:11]
	s_mov_b32 s10, 0x283ff000
	v_add_co_u32_e32 v4, vcc, s10, v4
	s_waitcnt lgkmcnt(0)
	v_pk_add_f32 v[28:29], v[28:29], v[30:31]
	v_addc_co_u32_e32 v5, vcc, 0, v5, vcc
	v_pk_add_f32 v[26:27], v[2:3], v[26:27]
	v_pk_add_f32 v[2:3], v[24:25], v[0:1]
	v_pk_add_f32 v[0:1], v[20:21], v[22:23]
	v_pk_add_f32 v[16:17], v[16:17], v[18:19]
	v_pk_add_f32 v[14:15], v[12:13], v[14:15]
	global_store_dwordx4 v[4:5], v[6:9], off nt
	global_store_dwordx4 v[10:11], v[14:17], off offset:16 nt
	global_store_dwordx4 v[10:11], v[0:3], off offset:512 nt
	global_store_dwordx4 v[10:11], v[26:29], off offset:528 nt
